# all four GEMM phases tile rows 0..16383 as 16 m-tiles per XCD with 32x32 K-split tail blocks for rows 16384+ (phase 1 EPI0 tail added); phase 1: first-dispatched WGs 8 tiles, second-dispatched 5
# speedup vs baseline: 1.0037x; 1.0037x over previous
.LBB0_123:
	s_or_b64 exec, exec, s[0:1]
	v_readlane_b32 s0, v252, 0
	v_readlane_b32 s1, v252, 1
	s_add_u32 s0, s0, 0x12ab700
	s_addc_u32 s1, s1, 0
	v_writelane_b32 v252, s0, 37
	s_and_b32 s30, s78, 7
	s_ashr_i32 s6, s78, 3
	v_writelane_b32 v252, s1, 38
	s_mov_b32 s4, s6
	v_readlane_b32 s0, v252, 2
	s_ashr_i32 s0, s0, 3
	v_readlane_b32 s1, v252, 3
	v_writelane_b32 v252, s0, 39
	s_mul_i32 s0, s30, 0x80
	s_lshr_b32 s1, s0, 3
	s_addk_i32 s0, 0x80
	s_lshr_b32 s0, s0, 3
	s_sub_i32 s5, s0, s1
	v_writelane_b32 v252, s1, 40
	s_lshl_b32 s1, s5, 3
	v_writelane_b32 v252, s1, 41
	s_mul_i32 s8, s5, 26
	v_writelane_b32 v252, s4, 42
	s_cmp_ge_i32 s6, s8
	s_mul_i32 s1, s5, 24
	v_writelane_b32 v252, s5, 43
	v_writelane_b32 v252, s5, 44
	s_waitcnt lgkmcnt(0)
	s_barrier
	v_writelane_b32 v252, s1, 45
	s_cbranch_scc1 .LBB0_138
	v_readlane_b32 s1, v252, 41
	s_abs_i32 s9, s1
	v_cvt_f32_u32_e32 v0, s9
	s_ashr_i32 s10, s1, 31
	v_readlane_b32 s1, v252, 40
	s_mul_i32 s1, s1, 24
	v_rcp_iflag_f32_e32 v0, v0
	s_mul_i32 s0, s0, 24
	v_readlane_b32 s4, v252, 44
	s_sub_i32 s11, 0, s4
	v_mul_f32_e32 v0, 0x4f7ffffe, v0
	v_cvt_u32_f32_e32 v0, v0
	s_sub_i32 s4, 0, s9
	s_sub_i32 s14, s1, s0
	v_mov_b32_e32 v65, 0
	v_readfirstlane_b32 s0, v0
	s_mul_i32 s4, s4, s0
	s_mul_hi_u32 s1, s0, s4
	s_add_i32 s15, s0, s1
	v_readlane_b32 s0, v252, 42
	s_mov_b32 s12, 0x10000
	s_mov_b32 s13, 0x20000
	s_mov_b32 s16, 0x30000
	s_movk_i32 s17, 0x1a00
	s_movk_i32 s18, 0x7fff
	s_movk_i32 s19, 0x4180
	s_mov_b64 s[4:5], 0x8853800
	s_mov_b32 s34, 0x5040100
	s_mov_b32 s35, 0x8853000
	v_mov_b32_e32 v84, 1
	s_cmp_lt_u32 s0, 32
	s_cselect_b32 s36, 0, 0xe0
	s_cselect_b32 s8, 0x100, s8
	s_add_i32 s36, s36, s0
	v_readlane_b32 s1, v252, 43
	s_branch .LBB0_126
.LBB0_125:
	s_add_i32 s36, s36, 32
	s_cmp_lt_i32 s36, s8
	s_cbranch_scc0 .LBB0_138

.LBB0_138:
	s_mov_b32 s34, s78
.Ltail0_loop:
	s_barrier
	s_mov_b32 s0, s34
	s_cmpk_gt_u32 s0, 0x207
	s_cbranch_scc1 .Ltail0_end
	s_mul_i32 s1, s0, 0x277
	s_lshr_b32 s1, s1, 16
	s_mul_i32 s5, s1, 0x68
	s_sub_i32 s4, s0, s5
	v_readlane_b32 s18, v252, 0
	v_readlane_b32 s19, v252, 1
	s_lshl_b32 s5, s1, 16
	s_add_u32 s10, s18, s5
	s_addc_u32 s11, s19, 0
	s_add_u32 s10, s10, 0xc0e3700
	s_addc_u32 s11, s11, 0
	s_lshl_b32 s5, s4, 16
	s_mov_b64 s[12:13], s[18:19]
	s_add_u32 s12, s12, s5
	s_addc_u32 s13, s13, 0
	v_and_b32_e32 v66, 31, v218
	v_lshrrev_b32_e32 v77, 6, v218
	v_bfe_u32 v78, v218, 5, 1
	v_lshlrev_b32_e32 v79, 2, v66
	v_mov_b32_e32 v64, v66
	v_lshlrev_b32_e32 v66, 11, v66
	v_lshl_add_u32 v66, v77, 9, v66
	v_lshl_add_u32 v66, v78, 4, v66
	global_load_dwordx4 v[82:85], v66, s[10:11]
	global_load_dwordx4 v[16:19], v66, s[12:13]
	global_load_dwordx4 v[86:89], v66, s[10:11] offset:32
	global_load_dwordx4 v[20:23], v66, s[12:13] offset:32
	global_load_dwordx4 v[90:93], v66, s[10:11] offset:64
	global_load_dwordx4 v[24:27], v66, s[12:13] offset:64
	global_load_dwordx4 v[94:97], v66, s[10:11] offset:96
	global_load_dwordx4 v[28:31], v66, s[12:13] offset:96
	global_load_dwordx4 v[98:101], v66, s[10:11] offset:128
	global_load_dwordx4 v[32:35], v66, s[12:13] offset:128
	global_load_dwordx4 v[102:105], v66, s[10:11] offset:160
	global_load_dwordx4 v[36:39], v66, s[12:13] offset:160
	global_load_dwordx4 v[106:109], v66, s[10:11] offset:192
	global_load_dwordx4 v[40:43], v66, s[12:13] offset:192
	global_load_dwordx4 v[110:113], v66, s[10:11] offset:224
	global_load_dwordx4 v[44:47], v66, s[12:13] offset:224
	global_load_dwordx4 v[114:117], v66, s[10:11] offset:256
	global_load_dwordx4 v[48:51], v66, s[12:13] offset:256
	global_load_dwordx4 v[118:121], v66, s[10:11] offset:288
	global_load_dwordx4 v[52:55], v66, s[12:13] offset:288
	global_load_dwordx4 v[122:125], v66, s[10:11] offset:320
	global_load_dwordx4 v[56:59], v66, s[12:13] offset:320
	global_load_dwordx4 v[126:129], v66, s[10:11] offset:352
	global_load_dwordx4 v[60:63], v66, s[12:13] offset:352
	global_load_dwordx4 v[130:133], v66, s[10:11] offset:384
	global_load_dwordx4 v[150:153], v66, s[12:13] offset:384
	global_load_dwordx4 v[136:139], v66, s[10:11] offset:416
	global_load_dwordx4 v[154:157], v66, s[12:13] offset:416
	global_load_dwordx4 v[140:143], v66, s[10:11] offset:448
	global_load_dwordx4 v[158:161], v66, s[12:13] offset:448
	global_load_dwordx4 v[144:147], v66, s[10:11] offset:480
	global_load_dwordx4 v[162:165], v66, s[12:13] offset:480
	s_mul_i32 s5, s1, 0x34000
	s_add_u32 s14, s18, s5
	s_addc_u32 s15, s19, 0
	s_lshl_b32 s5, s4, 6
	s_add_i32 s5, s5, 0x7aab700
	s_add_u32 s14, s14, s5
	s_addc_u32 s15, s15, 0
	s_lshl_b32 s5, s4, 5
	s_sub_i32 s5, s5, 0x280
	s_mul_i32 s5, s5, 0x8300
	s_add_u32 s16, s18, s5
	s_addc_u32 s17, s19, 0
	s_lshl_b32 s5, s1, 6
	s_add_i32 s5, s5, 0x9cd3800
	s_add_u32 s16, s16, s5
	s_addc_u32 s17, s17, 0
	v_lshlrev_b32_e32 v67, 3, v77
	v_lshl_add_u32 v67, v78, 2, v67
	v_lshlrev_b32_e32 v71, 1, v67
	v_mul_u32_u24_e32 v67, 0x1a00, v67
	v_lshl_add_u32 v67, v64, 1, v67
	v_add_u32_e32 v68, 0x1a00, v67
	v_add_u32_e32 v69, 0x3400, v67
	v_add_u32_e32 v70, 0x4e00, v67
	v_mul_u32_u24_e32 v72, 0x8300, v64
	v_add_u32_e32 v71, v71, v72
	v_and_b32_e32 v75, 63, v218
	v_lshlrev_b32_e32 v75, 4, v75
	v_lshl_add_u32 v76, v77, 10, v75
	v_lshl_add_u32 v75, v77, 12, v75
	s_waitcnt vmcnt(30)
	v_mfma_f32_32x32x16_bf16 v[0:15], v[82:85], v[16:19], 0
	s_waitcnt vmcnt(28)
	v_mfma_f32_32x32x16_bf16 v[0:15], v[86:89], v[20:23], v[0:15]
	s_waitcnt vmcnt(26)
	v_mfma_f32_32x32x16_bf16 v[0:15], v[90:93], v[24:27], v[0:15]
	s_waitcnt vmcnt(24)
	v_mfma_f32_32x32x16_bf16 v[0:15], v[94:97], v[28:31], v[0:15]
	s_waitcnt vmcnt(22)
	v_mfma_f32_32x32x16_bf16 v[0:15], v[98:101], v[32:35], v[0:15]
	s_waitcnt vmcnt(20)
	v_mfma_f32_32x32x16_bf16 v[0:15], v[102:105], v[36:39], v[0:15]
	s_waitcnt vmcnt(18)
	v_mfma_f32_32x32x16_bf16 v[0:15], v[106:109], v[40:43], v[0:15]
	s_waitcnt vmcnt(16)
	v_mfma_f32_32x32x16_bf16 v[0:15], v[110:113], v[44:47], v[0:15]
	s_waitcnt vmcnt(14)
	v_mfma_f32_32x32x16_bf16 v[0:15], v[114:117], v[48:51], v[0:15]
	s_waitcnt vmcnt(12)
	v_mfma_f32_32x32x16_bf16 v[0:15], v[118:121], v[52:55], v[0:15]
	s_waitcnt vmcnt(10)
	v_mfma_f32_32x32x16_bf16 v[0:15], v[122:125], v[56:59], v[0:15]
	s_waitcnt vmcnt(8)
	v_mfma_f32_32x32x16_bf16 v[0:15], v[126:129], v[60:63], v[0:15]
	s_waitcnt vmcnt(6)
	v_mfma_f32_32x32x16_bf16 v[0:15], v[130:133], v[150:153], v[0:15]
	s_waitcnt vmcnt(4)
	v_mfma_f32_32x32x16_bf16 v[0:15], v[136:139], v[154:157], v[0:15]
	s_waitcnt vmcnt(2)
	v_mfma_f32_32x32x16_bf16 v[0:15], v[140:143], v[158:161], v[0:15]
	s_waitcnt vmcnt(0)
	v_mfma_f32_32x32x16_bf16 v[0:15], v[144:147], v[162:165], v[0:15]
	s_nop 15
	s_nop 15
	ds_write_b128 v75, v[0:3]
	ds_write_b128 v75, v[4:7] offset:1024
	ds_write_b128 v75, v[8:11] offset:2048
	ds_write_b128 v75, v[12:15] offset:3072
	s_waitcnt lgkmcnt(0)
	s_barrier
	ds_read_b128 v[16:19], v76
	ds_read_b128 v[20:23], v76 offset:4096
	ds_read_b128 v[24:27], v76 offset:8192
	ds_read_b128 v[28:31], v76 offset:12288
	s_waitcnt lgkmcnt(0)
	v_pk_add_f32 v[16:17], v[16:17], v[20:21]
	v_pk_add_f32 v[18:19], v[18:19], v[22:23]
	v_pk_add_f32 v[24:25], v[24:25], v[28:29]
	v_pk_add_f32 v[26:27], v[26:27], v[30:31]
	v_pk_add_f32 v[16:17], v[16:17], v[24:25]
	v_pk_add_f32 v[18:19], v[18:19], v[26:27]
	v_cvt_pk_bf16_f32 v20, v16, v17
	v_cvt_pk_bf16_f32 v21, v18, v19
	global_store_short v67, v20, s[14:15]
	global_store_short_d16_hi v68, v20, s[14:15]
	global_store_short v69, v21, s[14:15]
	global_store_short_d16_hi v70, v21, s[14:15]
	s_sub_i32 s5, s4, 20
	s_cmp_lt_u32 s5, 4
	s_cbranch_scc0 .Ltail0_nt
	global_store_dwordx2 v71, v[20:21], s[16:17]
.Ltail0_nt:
	s_add_i32 s34, s34, 0x200
	s_branch .Ltail0_loop

.Ltail2_nt:
.Ltail2_end:
	s_waitcnt vmcnt(0)
	v_readlane_b32 s4, v252, 31
	v_readlane_b32 s5, v252, 32
	s_waitcnt vmcnt(63) expcnt(7) lgkmcnt(15)
	s_barrier
	s_mov_b64 s[2:3], exec
	v_readlane_b32 s0, v252, 33
	v_readlane_b32 s1, v252, 34
	s_and_b64 s[0:1], s[2:3], s[0:1]
	s_mov_b64 exec, s[0:1]
	s_cbranch_execz .LBB0_1874
	s_waitcnt vmcnt(3)
	v_mov_b32_e32 v0, 0x12400
	ds_read_b32 v0, v0
	s_mov_b64 s[0:1], -1
	s_waitcnt lgkmcnt(0)
	v_cmp_eq_u32_e32 vcc, 0, v0
	s_cbranch_vccz .LBB0_1873
	s_waitcnt vmcnt(2)
	v_mbcnt_hi_u32_b32 v5, -1, v219
	v_and_b32_e32 v0, 64, v5
	v_add_u32_e32 v6, 64, v0
	v_xor_b32_e32 v0, 32, v5
	v_cmp_lt_i32_e32 vcc, v0, v6
	v_xor_b32_e32 v1, 16, v5
	v_xor_b32_e32 v2, 8, v5
	v_cndmask_b32_e32 v0, v5, v0, vcc
	v_cmp_lt_i32_e32 vcc, v1, v6
	v_xor_b32_e32 v3, 4, v5
	v_xor_b32_e32 v4, 2, v5
	v_cndmask_b32_e32 v1, v5, v1, vcc
	v_cmp_lt_i32_e32 vcc, v2, v6
	v_xor_b32_e32 v7, 1, v5
	v_lshlrev_b32_e32 v0, 2, v0
	v_cndmask_b32_e32 v2, v5, v2, vcc
	v_cmp_lt_i32_e32 vcc, v3, v6
	v_lshlrev_b32_e32 v1, 2, v1
	v_lshlrev_b32_e32 v2, 2, v2
	v_cndmask_b32_e32 v3, v5, v3, vcc
	v_cmp_lt_i32_e32 vcc, v4, v6
	v_lshlrev_b32_e32 v3, 2, v3
	s_mov_b64 s[4:5], 0
	v_cndmask_b32_e32 v4, v5, v4, vcc
	v_cmp_lt_i32_e32 vcc, v7, v6
	v_lshlrev_b32_e32 v4, 2, v4
	v_mov_b32_e32 v6, 0x100000
	v_cndmask_b32_e32 v5, v5, v7, vcc
	v_lshlrev_b32_e32 v5, 2, v5
	s_branch .LBB0_1866
